# nt hint on the norm1 and norm3 bf16 output stores (keep the f32 residual stream cached for the P3 and P12 epilogues)
# baseline (speedup 1.0000x reference)
; #define LAS __attribute__((address_space(3)))
; __device__ __forceinline__ unsigned pk2(float lo, float hi) { const f32x2c v = {lo, hi}; const bf16x2c b = __builtin_convertvector(v, bf16x2c); return __builtin_bit_cast(unsigned, b); }
; #define lane (lane_now())
; __device__ __forceinline__ void norm_phase(const float* src, const float* g, const float* mod, int ish, int isc, bf16_t* dst, LAS unsigned char* lds, int gw, int ngw, int wave, int lane) {
;     ...
;     for (int m = gw; m < MTOK; m += ngw) {
;         const f32x4* xr = (const f32x4*)(src + (size_t)m * DM) + lane;
;         f32x4 v[4]; float s = 0.f;
; #pragma unroll
;         for (int j = 0; j < 4; ++j) { v[j] = xr[64 * j]; s += (v[j].x * v[j].x + v[j].y * v[j].y) + (v[j].z * v[j].z + v[j].w * v[j].w); }
;         s = wave_sum(s);
;         const float rstd = rsqrtf(s * (1.f / DM) + 1e-6f);
;         const int bo = (m >> 13) * 1024;
;         u32x2* o8 = (u32x2*)(dst + (size_t)m * DM) + lane;
; #pragma unroll
;         for (int j = 0; j < 4; ++j) { const int c = bo + 4 * lane + 256 * j;
;             const f32x4 gg = *(const LAS f32x4*)(GSl + c), h4 = *(const LAS f32x4*)(SHl + c);
;             const f32x4 o = v[j] * rstd * gg + h4;
;             u32x2 w; w.x = pk2(o.x, o.y); w.y = pk2(o.z, o.w); o8[64 * j] = w; }
;     }
.LBB0_86:
	global_load_dwordx4 v[12:15], v[0:1], off offset:-3072
	global_load_dwordx4 v[16:19], v[0:1], off offset:-2048
	global_load_dwordx4 v[20:23], v[0:1], off offset:-1024
	global_load_dwordx4 v[24:27], v[0:1], off
	s_ashr_i32 s16, s11, 3
	s_and_b32 s16, s16, 0x3ffffc00
	v_add_u32_e32 v28, s16, v10
	v_lshl_add_u32 v56, v28, 2, 0
	ds_read_b128 v[28:31], v56
	ds_read_b128 v[32:35], v56 offset:1024
	ds_read_b128 v[36:39], v56 offset:16384
	ds_read_b128 v[40:43], v56 offset:17408
	ds_read_b128 v[44:47], v56 offset:2048
	ds_read_b128 v[48:51], v56 offset:3072
	ds_read_b128 v[52:55], v56 offset:18432
	ds_read_b128 v[56:59], v56 offset:19456
	s_add_i32 s11, s11, s84
	v_lshl_add_u64 v[0:1], v[0:1], 0, s[6:7]
	s_cmp_lt_i32 s11, s98
	s_waitcnt vmcnt(3)
	v_pk_mul_f32 v[60:61], v[14:15], v[14:15]
	v_pk_mul_f32 v[62:63], v[12:13], v[12:13]
	s_waitcnt vmcnt(2)
	v_pk_mul_f32 v[64:65], v[18:19], v[18:19]
	v_pk_mul_f32 v[66:67], v[16:17], v[16:17]
	v_pk_mov_b32 v[72:73], v[62:63], v[60:61] op_sel:[1,0]
	v_mov_b32_e32 v63, v61
	v_pk_mov_b32 v[60:61], v[66:67], v[64:65] op_sel:[1,0]
	v_mov_b32_e32 v67, v65
	s_waitcnt vmcnt(0)
	v_mul_f32_e32 v71, v24, v24
	v_mul_f32_e32 v68, v21, v21
	v_mul_f32_e32 v70, v23, v23
	v_pk_add_f32 v[62:63], v[72:73], v[62:63]
	v_pk_add_f32 v[60:61], v[60:61], v[66:67]
	v_mul_f32_e32 v74, v25, v25
	v_mul_f32_e32 v75, v26, v26
	v_mul_f32_e32 v76, v27, v27
	v_pk_fma_f32 v[64:65], v[20:21], v[20:21], v[68:69] op_sel_hi:[1,1,0]
	v_pk_fma_f32 v[68:69], v[22:23], v[22:23], v[70:71] op_sel_hi:[1,1,0]
	v_pk_add_f32 v[62:63], v[62:63], v[62:63] op_sel:[0,1] op_sel_hi:[1,0]
	v_pk_add_f32 v[60:61], v[60:61], v[60:61] op_sel:[0,1] op_sel_hi:[1,0]
	v_mov_b32_e32 v65, v75
	v_mov_b32_e32 v69, v76
	v_mov_b32_e32 v63, v71
	v_mov_b32_e32 v61, v74
	v_pk_add_f32 v[64:65], v[64:65], v[68:69]
	v_pk_add_f32 v[60:61], v[62:63], v[60:61]
	s_nop 0
	v_pk_add_f32 v[60:61], v[60:61], v[64:65]
	s_nop 0
	v_add_f32_e32 v60, v60, v61
	ds_bpermute_b32 v61, v4, v60
	s_waitcnt lgkmcnt(0)
	v_add_f32_e32 v60, v60, v61
	ds_bpermute_b32 v61, v5, v60
	s_waitcnt lgkmcnt(0)
	v_add_f32_e32 v60, v60, v61
	ds_bpermute_b32 v61, v6, v60
	s_waitcnt lgkmcnt(0)
	v_add_f32_e32 v60, v60, v61
	ds_bpermute_b32 v61, v7, v60
	s_waitcnt lgkmcnt(0)
	v_add_f32_e32 v60, v60, v61
	ds_bpermute_b32 v61, v8, v60
	s_waitcnt lgkmcnt(0)
	v_add_f32_e32 v60, v60, v61
	ds_bpermute_b32 v61, v9, v60
	s_waitcnt lgkmcnt(0)
	v_add_f32_e32 v60, v60, v61
	v_fmamk_f32 v60, v60, 0x3a800000, v11
	v_mul_f32_e32 v61, 0x4b800000, v60
	v_cmp_gt_f32_e32 vcc, s10, v60
	s_nop 1
	v_cndmask_b32_e32 v60, v60, v61, vcc
	v_rsq_f32_e32 v60, v60
	s_nop 0
	v_mul_f32_e32 v61, 0x45800000, v60
	v_cndmask_b32_e32 v60, v60, v61, vcc
	v_pk_mul_f32 v[12:13], v[12:13], v[60:61] op_sel_hi:[1,0]
	v_pk_mul_f32 v[14:15], v[14:15], v[60:61] op_sel_hi:[1,0]
	v_pk_mul_f32 v[16:17], v[16:17], v[60:61] op_sel_hi:[1,0]
	v_pk_mul_f32 v[18:19], v[18:19], v[60:61] op_sel_hi:[1,0]
	v_pk_mul_f32 v[20:21], v[20:21], v[60:61] op_sel_hi:[1,0]
	v_pk_mul_f32 v[22:23], v[22:23], v[60:61] op_sel_hi:[1,0]
	v_pk_mul_f32 v[24:25], v[24:25], v[60:61] op_sel_hi:[1,0]
	v_pk_mul_f32 v[26:27], v[26:27], v[60:61] op_sel_hi:[1,0]
	v_pk_fma_f32 v[14:15], v[30:31], v[14:15], v[38:39]
	v_pk_fma_f32 v[12:13], v[28:29], v[12:13], v[36:37]
	v_pk_fma_f32 v[18:19], v[34:35], v[18:19], v[42:43]
	v_pk_fma_f32 v[16:17], v[32:33], v[16:17], v[40:41]
	v_pk_fma_f32 v[22:23], v[46:47], v[22:23], v[54:55]
	v_pk_fma_f32 v[20:21], v[44:45], v[20:21], v[52:53]
	v_pk_fma_f32 v[26:27], v[50:51], v[26:27], v[58:59]
	v_pk_fma_f32 v[24:25], v[48:49], v[24:25], v[56:57]
	v_cvt_pk_bf16_f32 v12, v12, v13
	v_cvt_pk_bf16_f32 v13, v14, v15
	v_cvt_pk_bf16_f32 v14, v16, v17
	v_cvt_pk_bf16_f32 v15, v18, v19
	v_cvt_pk_bf16_f32 v16, v20, v21
	v_cvt_pk_bf16_f32 v17, v22, v23
	v_cvt_pk_bf16_f32 v18, v24, v25
	v_cvt_pk_bf16_f32 v19, v26, v27
	global_store_dwordx2 v[2:3], v[12:13], off nt
	global_store_dwordx2 v[2:3], v[14:15], off offset:512 nt
	global_store_dwordx2 v[2:3], v[16:17], off offset:1024 nt
	global_store_dwordx2 v[2:3], v[18:19], off offset:1536 nt
	v_lshl_add_u64 v[2:3], v[2:3], 0, s[4:5]
	s_cbranch_scc1 .LBB0_86
	s_mov_b32 s78, s100
	s_mov_b32 s84, s101

; #define LAS __attribute__((address_space(3)))
; __device__ __forceinline__ unsigned pk2(float lo, float hi) { const f32x2c v = {lo, hi}; const bf16x2c b = __builtin_convertvector(v, bf16x2c); return __builtin_bit_cast(unsigned, b); }
; #define lane (lane_now())
; __device__ __forceinline__ void norm_phase(const float* src, const float* g, const float* mod, int ish, int isc, bf16_t* dst, LAS unsigned char* lds, int gw, int ngw, int wave, int lane) {
;     ...
;     for (int m = gw; m < MTOK; m += ngw) {
;         const f32x4* xr = (const f32x4*)(src + (size_t)m * DM) + lane;
;         f32x4 v[4]; float s = 0.f;
; #pragma unroll
;         for (int j = 0; j < 4; ++j) { v[j] = xr[64 * j]; s += (v[j].x * v[j].x + v[j].y * v[j].y) + (v[j].z * v[j].z + v[j].w * v[j].w); }
;         s = wave_sum(s);
;         const float rstd = rsqrtf(s * (1.f / DM) + 1e-6f);
;         const int bo = (m >> 13) * 1024;
;         u32x2* o8 = (u32x2*)(dst + (size_t)m * DM) + lane;
; #pragma unroll
;         for (int j = 0; j < 4; ++j) { const int c = bo + 4 * lane + 256 * j;
;             const f32x4 gg = *(const LAS f32x4*)(GSl + c), h4 = *(const LAS f32x4*)(SHl + c);
;             const f32x4 o = v[j] * rstd * gg + h4;
;             u32x2 w; w.x = pk2(o.x, o.y); w.y = pk2(o.z, o.w); o8[64 * j] = w; }
;     }
.LBB0_1247:
	global_load_dwordx4 v[12:15], v[0:1], off offset:-3072
	global_load_dwordx4 v[16:19], v[0:1], off offset:-2048
	global_load_dwordx4 v[20:23], v[0:1], off offset:-1024
	global_load_dwordx4 v[24:27], v[0:1], off
	s_ashr_i32 s9, s78, 3
	s_and_b32 s9, s9, 0x3ffffc00
	v_add_u32_e32 v28, s9, v10
	v_lshl_add_u32 v56, v28, 2, 0
	ds_read_b128 v[28:31], v56
	ds_read_b128 v[32:35], v56 offset:1024
	ds_read_b128 v[36:39], v56 offset:16384
	ds_read_b128 v[40:43], v56 offset:17408
	ds_read_b128 v[44:47], v56 offset:2048
	ds_read_b128 v[48:51], v56 offset:3072
	ds_read_b128 v[52:55], v56 offset:18432
	ds_read_b128 v[56:59], v56 offset:19456
	s_add_i32 s78, s78, s84
	v_lshl_add_u64 v[0:1], v[0:1], 0, s[6:7]
	s_cmp_lt_i32 s78, s98
	s_waitcnt vmcnt(3)
	v_pk_mul_f32 v[60:61], v[14:15], v[14:15]
	v_pk_mul_f32 v[62:63], v[12:13], v[12:13]
	s_waitcnt vmcnt(2)
	v_pk_mul_f32 v[64:65], v[18:19], v[18:19]
	v_pk_mul_f32 v[66:67], v[16:17], v[16:17]
	v_pk_mov_b32 v[72:73], v[62:63], v[60:61] op_sel:[1,0]
	v_mov_b32_e32 v63, v61
	v_pk_mov_b32 v[60:61], v[66:67], v[64:65] op_sel:[1,0]
	v_mov_b32_e32 v67, v65
	s_waitcnt vmcnt(0)
	v_mul_f32_e32 v71, v24, v24
	v_mul_f32_e32 v68, v21, v21
	v_mul_f32_e32 v70, v23, v23
	v_pk_add_f32 v[62:63], v[72:73], v[62:63]
	v_pk_add_f32 v[60:61], v[60:61], v[66:67]
	v_mul_f32_e32 v74, v25, v25
	v_mul_f32_e32 v75, v26, v26
	v_mul_f32_e32 v76, v27, v27
	v_pk_fma_f32 v[64:65], v[20:21], v[20:21], v[68:69] op_sel_hi:[1,1,0]
	v_pk_fma_f32 v[68:69], v[22:23], v[22:23], v[70:71] op_sel_hi:[1,1,0]
	v_pk_add_f32 v[62:63], v[62:63], v[62:63] op_sel:[0,1] op_sel_hi:[1,0]
	v_pk_add_f32 v[60:61], v[60:61], v[60:61] op_sel:[0,1] op_sel_hi:[1,0]
	v_mov_b32_e32 v65, v75
	v_mov_b32_e32 v69, v76
	v_mov_b32_e32 v63, v71
	v_mov_b32_e32 v61, v74
	v_pk_add_f32 v[64:65], v[64:65], v[68:69]
	v_pk_add_f32 v[60:61], v[62:63], v[60:61]
	s_nop 0
	v_pk_add_f32 v[60:61], v[60:61], v[64:65]
	s_nop 0
	v_add_f32_e32 v60, v60, v61
	ds_bpermute_b32 v61, v4, v60
	s_waitcnt lgkmcnt(0)
	v_add_f32_e32 v60, v60, v61
	ds_bpermute_b32 v61, v5, v60
	s_waitcnt lgkmcnt(0)
	v_add_f32_e32 v60, v60, v61
	ds_bpermute_b32 v61, v6, v60
	s_waitcnt lgkmcnt(0)
	v_add_f32_e32 v60, v60, v61
	ds_bpermute_b32 v61, v7, v60
	s_waitcnt lgkmcnt(0)
	v_add_f32_e32 v60, v60, v61
	ds_bpermute_b32 v61, v8, v60
	s_waitcnt lgkmcnt(0)
	v_add_f32_e32 v60, v60, v61
	ds_bpermute_b32 v61, v9, v60
	s_waitcnt lgkmcnt(0)
	v_add_f32_e32 v60, v60, v61
	v_fmamk_f32 v60, v60, 0x3a800000, v11
	v_mul_f32_e32 v61, 0x4b800000, v60
	v_cmp_gt_f32_e32 vcc, s8, v60
	s_nop 1
	v_cndmask_b32_e32 v60, v60, v61, vcc
	v_rsq_f32_e32 v60, v60
	s_nop 0
	v_mul_f32_e32 v61, 0x45800000, v60
	v_cndmask_b32_e32 v60, v60, v61, vcc
	v_pk_mul_f32 v[12:13], v[12:13], v[60:61] op_sel_hi:[1,0]
	v_pk_mul_f32 v[14:15], v[14:15], v[60:61] op_sel_hi:[1,0]
	v_pk_mul_f32 v[16:17], v[16:17], v[60:61] op_sel_hi:[1,0]
	v_pk_mul_f32 v[18:19], v[18:19], v[60:61] op_sel_hi:[1,0]
	v_pk_mul_f32 v[20:21], v[20:21], v[60:61] op_sel_hi:[1,0]
	v_pk_mul_f32 v[22:23], v[22:23], v[60:61] op_sel_hi:[1,0]
	v_pk_mul_f32 v[24:25], v[24:25], v[60:61] op_sel_hi:[1,0]
	v_pk_mul_f32 v[26:27], v[26:27], v[60:61] op_sel_hi:[1,0]
	v_pk_fma_f32 v[14:15], v[30:31], v[14:15], v[38:39]
	v_pk_fma_f32 v[12:13], v[28:29], v[12:13], v[36:37]
	v_pk_fma_f32 v[18:19], v[34:35], v[18:19], v[42:43]
	v_pk_fma_f32 v[16:17], v[32:33], v[16:17], v[40:41]
	v_pk_fma_f32 v[22:23], v[46:47], v[22:23], v[54:55]
	v_pk_fma_f32 v[20:21], v[44:45], v[20:21], v[52:53]
	v_pk_fma_f32 v[26:27], v[50:51], v[26:27], v[58:59]
	v_pk_fma_f32 v[24:25], v[48:49], v[24:25], v[56:57]
	v_cvt_pk_bf16_f32 v12, v12, v13
	v_cvt_pk_bf16_f32 v13, v14, v15
	v_cvt_pk_bf16_f32 v14, v16, v17
	v_cvt_pk_bf16_f32 v15, v18, v19
	v_cvt_pk_bf16_f32 v16, v20, v21
	v_cvt_pk_bf16_f32 v17, v22, v23
	v_cvt_pk_bf16_f32 v18, v24, v25
	v_cvt_pk_bf16_f32 v19, v26, v27
	global_store_dwordx2 v[2:3], v[12:13], off nt
	global_store_dwordx2 v[2:3], v[14:15], off offset:512 nt
	global_store_dwordx2 v[2:3], v[16:17], off offset:1024 nt
	global_store_dwordx2 v[2:3], v[18:19], off offset:1536 nt
	v_lshl_add_u64 v[2:3], v[2:3], 0, s[0:1]
	s_cbranch_scc1 .LBB0_1247
	s_add_i32 s78, s100, 0x8000
	s_mov_b32 s84, s101
